# v34 + nt hint on the fp8/bf16 activation stores of the two layer-0 LayerNorm phases
# baseline (speedup 1.0000x reference)
.Lln5_skip:
	v_pk_mov_b32 v[46:47], v[30:31], v[32:33] op_sel:[1,0]
	v_mov_b32_e32 v48, v30
	v_mov_b32_e32 v49, v33
	v_pk_mov_b32 v[50:51], v[34:35], v[36:37] op_sel:[1,0]
	v_mov_b32_e32 v52, v34
	v_mov_b32_e32 v53, v37
	v_pk_add_f32 v[46:47], v[46:47], v[48:49]
	v_pk_add_f32 v[48:49], v[50:51], v[52:53]
	v_add_f32_e32 v21, v46, v47
	v_pk_add_f32 v[46:47], v[48:49], v[48:49] op_sel:[0,1] op_sel_hi:[1,0]
	v_add_f32_e32 v54, v38, v39
	v_add_f32_e32 v56, v40, v41
	v_mov_b32_e32 v59, v42
	v_mov_b32_e32 v55, v44
	v_mov_b32_e32 v57, v45
	v_add_f32_e32 v58, 0, v21
	v_mov_b32_e32 v47, v43
	v_pk_add_f32 v[50:51], v[54:55], v[56:57]
	v_pk_add_f32 v[46:47], v[58:59], v[46:47]
	s_nop 0
	v_pk_add_f32 v[46:47], v[46:47], v[50:51]
	s_nop 0
	v_add_f32_e32 v21, v46, v47
	ds_bpermute_b32 v46, v12, v21
	s_waitcnt lgkmcnt(0)
	v_add_f32_e32 v21, v21, v46
	ds_bpermute_b32 v46, v13, v21
	s_waitcnt lgkmcnt(0)
	v_add_f32_e32 v21, v21, v46
	ds_bpermute_b32 v46, v14, v21
	s_waitcnt lgkmcnt(0)
	v_add_f32_e32 v21, v21, v46
	ds_bpermute_b32 v46, v15, v21
	s_waitcnt lgkmcnt(0)
	v_add_f32_e32 v21, v21, v46
	ds_bpermute_b32 v46, v16, v21
	s_waitcnt lgkmcnt(0)
	v_add_f32_e32 v21, v21, v46
	ds_bpermute_b32 v46, v17, v21
	s_waitcnt lgkmcnt(0)
	v_add_f32_e32 v21, v21, v46
	v_fmamk_f32 v31, v21, 0xba800000, v31
	v_fmac_f32_e32 v30, 0xba800000, v21
	v_fmamk_f32 v33, v21, 0xba800000, v33
	v_fmac_f32_e32 v32, 0xba800000, v21
	v_fmamk_f32 v35, v21, 0xba800000, v35
	v_fmac_f32_e32 v34, 0xba800000, v21
	v_fmamk_f32 v37, v21, 0xba800000, v37
	v_fmac_f32_e32 v36, 0xba800000, v21
	v_pk_mul_f32 v[46:47], v[32:33], v[32:33]
	v_pk_mul_f32 v[48:49], v[30:31], v[30:31]
	v_pk_mul_f32 v[50:51], v[36:37], v[36:37]
	v_pk_mul_f32 v[52:53], v[34:35], v[34:35]
	v_fmac_f32_e32 v38, 0xba800000, v21
	v_fmac_f32_e32 v40, 0xba800000, v21
	v_pk_mov_b32 v[58:59], v[48:49], v[46:47] op_sel:[1,0]
	v_mov_b32_e32 v49, v47
	v_pk_mov_b32 v[46:47], v[52:53], v[50:51] op_sel:[1,0]
	v_mov_b32_e32 v53, v51
	v_fmamk_f32 v39, v21, 0xba800000, v39
	v_fmamk_f32 v41, v21, 0xba800000, v41
	v_mul_f32_e32 v54, v38, v38
	v_mul_f32_e32 v56, v40, v40
	v_pk_add_f32 v[48:49], v[58:59], v[48:49]
	v_pk_add_f32 v[46:47], v[46:47], v[52:53]
	v_fmamk_f32 v45, v21, 0xba800000, v45
	v_fmac_f32_e32 v44, 0xba800000, v21
	v_fmamk_f32 v43, v21, 0xba800000, v43
	v_fmac_f32_e32 v42, 0xba800000, v21
	v_pk_fma_f32 v[50:51], v[38:39], v[38:39], v[54:55] op_sel_hi:[1,1,0]
	v_pk_fma_f32 v[54:55], v[40:41], v[40:41], v[56:57] op_sel_hi:[1,1,0]
	v_pk_add_f32 v[48:49], v[48:49], v[48:49] op_sel_hi:[0,1]
	v_pk_add_f32 v[46:47], v[46:47], v[46:47] op_sel_hi:[0,1]
	v_mul_f32_e32 v50, v42, v42
	v_mul_f32_e32 v54, v43, v43
	v_mul_f32_e32 v48, v44, v44
	v_mul_f32_e32 v46, v45, v45
	v_pk_add_f32 v[50:51], v[50:51], v[54:55]
	v_pk_add_f32 v[46:47], v[48:49], v[46:47]
	s_nop 0
	v_pk_add_f32 v[46:47], v[50:51], v[46:47]
	v_mov_b32_e32 v51, 0
	v_add_f32_e32 v21, v46, v47
	ds_bpermute_b32 v46, v12, v21
	s_waitcnt lgkmcnt(0)
	v_add_f32_e32 v21, v21, v46
	ds_bpermute_b32 v46, v13, v21
	s_waitcnt lgkmcnt(0)
	v_add_f32_e32 v21, v21, v46
	ds_bpermute_b32 v46, v14, v21
	s_waitcnt lgkmcnt(0)
	v_add_f32_e32 v21, v21, v46
	ds_bpermute_b32 v46, v15, v21
	s_waitcnt lgkmcnt(0)
	v_add_f32_e32 v21, v21, v46
	ds_bpermute_b32 v46, v16, v21
	s_waitcnt lgkmcnt(0)
	v_add_f32_e32 v21, v21, v46
	ds_bpermute_b32 v46, v17, v21
	s_waitcnt lgkmcnt(0)
	v_add_f32_e32 v21, v21, v46
	v_fmamk_f32 v21, v21, 0x3a800000, v18
	v_mul_f32_e32 v46, 0x4f800000, v21
	v_cmp_gt_f32_e32 vcc, s3, v21
	s_nop 1
	v_cndmask_b32_e32 v21, v21, v46, vcc
	v_sqrt_f32_e32 v46, v21
	s_nop 0
	v_add_u32_e32 v47, -1, v46
	v_add_u32_e32 v48, 1, v46
	v_fma_f32 v49, -v47, v46, v21
	v_fma_f32 v50, -v48, v46, v21
	v_cmp_ge_f32_e64 s[0:1], 0, v49
	s_nop 1
	v_cndmask_b32_e64 v46, v46, v47, s[0:1]
	v_cmp_lt_f32_e64 s[0:1], 0, v50
	s_nop 1
	v_cndmask_b32_e64 v46, v46, v48, s[0:1]
	v_mul_f32_e32 v47, 0x37800000, v46
	v_cndmask_b32_e32 v46, v46, v47, vcc
	v_cmp_class_f32_e32 vcc, v21, v19
	s_nop 1
	v_cndmask_b32_e32 v21, v46, v21, vcc
	v_div_scale_f32 v46, s[0:1], v21, v21, 1.0
	v_rcp_f32_e32 v48, v46
	v_div_scale_f32 v47, vcc, 1.0, v21, 1.0
	v_fma_f32 v49, -v46, v48, 1.0
	v_fmac_f32_e32 v48, v49, v48
	v_mul_f32_e32 v49, v47, v48
	v_fma_f32 v50, -v46, v49, v47
	v_fmac_f32_e32 v49, v50, v48
	v_fma_f32 v46, -v46, v49, v47
	v_div_fmas_f32 v46, v46, v48, v49
	v_div_fixup_f32 v46, v46, v21, 1.0
	v_pk_mul_f32 v[30:31], v[30:31], v[46:47] op_sel_hi:[1,0]
	v_pk_mul_f32 v[32:33], v[32:33], v[46:47] op_sel_hi:[1,0]
	v_pk_fma_f32 v[22:23], v[64:65], v[30:31], v[80:81]
	v_pk_fma_f32 v[24:25], v[66:67], v[32:33], v[82:83]
	global_store_dwordx4 v[10:11], v[22:25], off nt
	v_pk_mul_f32 v[34:35], v[34:35], v[46:47] op_sel_hi:[1,0]
	v_pk_mul_f32 v[36:37], v[36:37], v[46:47] op_sel_hi:[1,0]
	v_pk_mul_f32 v[38:39], v[38:39], v[46:47] op_sel_hi:[1,0]
	v_pk_mul_f32 v[40:41], v[40:41], v[46:47] op_sel_hi:[1,0]
	v_mov_b32_e32 v21, 0
	v_med3_f32 v22, v22, s12, v20
	v_med3_f32 v23, v23, s12, v20
	v_mov_b32_e32 v47, 0
	v_cvt_pk_fp8_f32 v21, v22, v23
	v_mov_b32_e32 v50, 0
	v_pk_mul_f32 v[42:43], v[42:43], v[46:47] op_sel_hi:[1,0]
	v_pk_mul_f32 v[44:45], v[44:45], v[46:47] op_sel_hi:[1,0]
	v_med3_f32 v24, v24, s12, v20
	v_med3_f32 v25, v25, s12, v20
	v_cvt_pk_fp8_f32 v21, v24, v25 op_sel:[0,0,1]
	v_lshl_add_u64 v[48:49], s[84:85], 0, v[4:5]
	v_add_co_u32_e32 v48, vcc, s13, v48
	v_lshl_add_u64 v[4:5], v[4:5], 0, s[4:5]
	s_nop 0
	v_addc_co_u32_e32 v49, vcc, 0, v49, vcc
	v_pk_fma_f32 v[28:29], v[70:71], v[36:37], v[86:87]
	v_pk_fma_f32 v[26:27], v[68:69], v[34:35], v[84:85]
	global_store_dwordx4 v[10:11], v[26:29], off offset:1024 nt
	v_med3_f32 v22, v26, s12, v20
	v_med3_f32 v23, v27, s12, v20
	v_cvt_pk_fp8_f32 v47, v22, v23
	v_med3_f32 v24, v28, s12, v20
	v_med3_f32 v25, v29, s12, v20
	v_cvt_pk_fp8_f32 v47, v24, v25 op_sel:[0,0,1]
	v_pk_fma_f32 v[32:33], v[74:75], v[40:41], v[90:91]
	v_pk_fma_f32 v[30:31], v[72:73], v[38:39], v[88:89]
	global_store_dwordx4 v[10:11], v[30:33], off offset:2048 nt
	v_med3_f32 v22, v30, s12, v20
	v_med3_f32 v23, v31, s12, v20
	v_cvt_pk_fp8_f32 v50, v22, v23
	v_med3_f32 v24, v32, s12, v20
	v_med3_f32 v25, v33, s12, v20
	v_cvt_pk_fp8_f32 v50, v24, v25 op_sel:[0,0,1]
	v_pk_fma_f32 v[22:23], v[76:77], v[42:43], v[92:93]
	s_nop 0
	v_med3_f32 v26, v22, s12, v20
	v_med3_f32 v27, v23, s12, v20
	v_cvt_pk_fp8_f32 v51, v26, v27
	v_pk_fma_f32 v[24:25], v[78:79], v[44:45], v[94:95]
	global_store_dwordx4 v[10:11], v[22:25], off offset:3072 nt
	v_med3_f32 v10, v24, s12, v20
	v_med3_f32 v11, v25, s12, v20
	v_cvt_pk_fp8_f32 v51, v10, v11 op_sel:[0,0,1]
	global_store_dword v[48:49], v21, off nt
	global_store_dword v[48:49], v47, off offset:256 nt
	global_store_dword v[48:49], v50, off offset:512 nt
	global_store_dword v[48:49], v51, off offset:768 nt
	s_cbranch_scc1 .LBB0_521
	v_readlane_b32 s81, v234, 49

.Lln8_skip:
	v_pk_mov_b32 v[44:45], v[24:25], v[26:27] op_sel:[1,0]
	v_mov_b32_e32 v46, v24
	v_mov_b32_e32 v47, v27
	v_pk_mov_b32 v[48:49], v[28:29], v[30:31] op_sel:[1,0]
	v_mov_b32_e32 v50, v28
	v_mov_b32_e32 v51, v31
	v_pk_add_f32 v[44:45], v[44:45], v[46:47]
	v_pk_add_f32 v[46:47], v[48:49], v[50:51]
	v_add_f32_e32 v50, v44, v45
	v_pk_add_f32 v[44:45], v[46:47], v[46:47] op_sel:[0,1] op_sel_hi:[1,0]
	v_add_f32_e32 v52, v32, v33
	v_add_f32_e32 v54, v34, v35
	v_mov_b32_e32 v57, v36
	v_mov_b32_e32 v53, v38
	v_mov_b32_e32 v55, v39
	v_add_f32_e32 v56, 0, v50
	v_mov_b32_e32 v45, v37
	v_pk_add_f32 v[48:49], v[52:53], v[54:55]
	v_pk_add_f32 v[44:45], v[56:57], v[44:45]
	s_nop 0
	v_pk_add_f32 v[44:45], v[44:45], v[48:49]
	s_nop 0
	v_add_f32_e32 v44, v44, v45
	ds_bpermute_b32 v45, v8, v44
	s_waitcnt lgkmcnt(0)
	v_add_f32_e32 v44, v44, v45
	ds_bpermute_b32 v45, v9, v44
	s_waitcnt lgkmcnt(0)
	v_add_f32_e32 v44, v44, v45
	ds_bpermute_b32 v45, v10, v44
	s_waitcnt lgkmcnt(0)
	v_add_f32_e32 v44, v44, v45
	ds_bpermute_b32 v45, v11, v44
	s_waitcnt lgkmcnt(0)
	v_add_f32_e32 v44, v44, v45
	ds_bpermute_b32 v45, v12, v44
	s_waitcnt lgkmcnt(0)
	v_add_f32_e32 v44, v44, v45
	ds_bpermute_b32 v45, v13, v44
	s_waitcnt lgkmcnt(0)
	v_add_f32_e32 v44, v44, v45
	v_fmamk_f32 v25, v44, 0xba800000, v25
	v_fmac_f32_e32 v24, 0xba800000, v44
	v_fmamk_f32 v27, v44, 0xba800000, v27
	v_fmac_f32_e32 v26, 0xba800000, v44
	v_fmamk_f32 v29, v44, 0xba800000, v29
	v_fmac_f32_e32 v28, 0xba800000, v44
	v_fmamk_f32 v31, v44, 0xba800000, v31
	v_fmac_f32_e32 v30, 0xba800000, v44
	v_fmamk_f32 v33, v44, 0xba800000, v33
	v_fmac_f32_e32 v32, 0xba800000, v44
	v_fmamk_f32 v35, v44, 0xba800000, v35
	v_fmac_f32_e32 v34, 0xba800000, v44
	v_fmamk_f32 v39, v44, 0xba800000, v39
	v_fmac_f32_e32 v38, 0xba800000, v44
	v_fmamk_f32 v37, v44, 0xba800000, v37
	v_fmac_f32_e32 v36, 0xba800000, v44
	v_pk_mul_f32 v[44:45], v[26:27], v[26:27]
	v_pk_mul_f32 v[46:47], v[24:25], v[24:25]
	v_pk_mul_f32 v[48:49], v[30:31], v[30:31]
	v_pk_mul_f32 v[50:51], v[28:29], v[28:29]
	v_pk_mov_b32 v[56:57], v[46:47], v[44:45] op_sel:[1,0]
	v_mov_b32_e32 v47, v45
	v_pk_mov_b32 v[44:45], v[50:51], v[48:49] op_sel:[1,0]
	v_mov_b32_e32 v51, v49
	v_mul_f32_e32 v52, v32, v32
	v_mul_f32_e32 v54, v34, v34
	v_pk_add_f32 v[46:47], v[56:57], v[46:47]
	v_pk_add_f32 v[44:45], v[44:45], v[50:51]
	v_pk_fma_f32 v[48:49], v[32:33], v[32:33], v[52:53] op_sel_hi:[1,1,0]
	v_pk_fma_f32 v[52:53], v[34:35], v[34:35], v[54:55] op_sel_hi:[1,1,0]
	v_pk_add_f32 v[46:47], v[46:47], v[46:47] op_sel_hi:[0,1]
	v_pk_add_f32 v[44:45], v[44:45], v[44:45] op_sel_hi:[0,1]
	v_mul_f32_e32 v48, v36, v36
	v_mul_f32_e32 v52, v37, v37
	v_mul_f32_e32 v46, v38, v38
	v_mul_f32_e32 v44, v39, v39
	v_pk_add_f32 v[48:49], v[48:49], v[52:53]
	v_pk_add_f32 v[44:45], v[46:47], v[44:45]
	s_nop 0
	v_pk_add_f32 v[44:45], v[48:49], v[44:45]
	s_nop 0
	v_add_f32_e32 v44, v44, v45
	ds_bpermute_b32 v45, v8, v44
	s_waitcnt lgkmcnt(0)
	v_add_f32_e32 v44, v44, v45
	ds_bpermute_b32 v45, v9, v44
	s_waitcnt lgkmcnt(0)
	v_add_f32_e32 v44, v44, v45
	ds_bpermute_b32 v45, v10, v44
	s_waitcnt lgkmcnt(0)
	v_add_f32_e32 v44, v44, v45
	ds_bpermute_b32 v45, v11, v44
	s_waitcnt lgkmcnt(0)
	v_add_f32_e32 v44, v44, v45
	ds_bpermute_b32 v45, v12, v44
	s_waitcnt lgkmcnt(0)
	v_add_f32_e32 v44, v44, v45
	ds_bpermute_b32 v45, v13, v44
	s_waitcnt lgkmcnt(0)
	v_add_f32_e32 v44, v44, v45
	v_fmamk_f32 v44, v44, 0x3a800000, v14
	v_mul_f32_e32 v45, 0x4f800000, v44
	v_cmp_gt_f32_e32 vcc, s3, v44
	s_nop 1
	v_cndmask_b32_e32 v44, v44, v45, vcc
	v_sqrt_f32_e32 v45, v44
	s_nop 0
	v_add_u32_e32 v46, -1, v45
	v_add_u32_e32 v47, 1, v45
	v_fma_f32 v48, -v46, v45, v44
	v_fma_f32 v49, -v47, v45, v44
	v_cmp_ge_f32_e64 s[0:1], 0, v48
	s_nop 1
	v_cndmask_b32_e64 v45, v45, v46, s[0:1]
	v_cmp_lt_f32_e64 s[0:1], 0, v49
	s_nop 1
	v_cndmask_b32_e64 v45, v45, v47, s[0:1]
	v_mul_f32_e32 v46, 0x37800000, v45
	v_cndmask_b32_e32 v45, v45, v46, vcc
	v_cmp_class_f32_e32 vcc, v44, v15
	s_nop 1
	v_cndmask_b32_e32 v44, v45, v44, vcc
	v_div_scale_f32 v45, s[0:1], v44, v44, 1.0
	v_rcp_f32_e32 v47, v45
	v_div_scale_f32 v46, vcc, 1.0, v44, 1.0
	v_fma_f32 v48, -v45, v47, 1.0
	v_fmac_f32_e32 v47, v48, v47
	v_mul_f32_e32 v48, v46, v47
	v_fma_f32 v49, -v45, v48, v46
	v_fmac_f32_e32 v48, v49, v47
	v_fma_f32 v45, -v45, v48, v46
	v_div_fmas_f32 v45, v45, v47, v48
	v_div_fixup_f32 v44, v45, v44, 1.0
	v_pk_mul_f32 v[24:25], v[24:25], v[44:45] op_sel_hi:[1,0]
	v_pk_mul_f32 v[26:27], v[26:27], v[44:45] op_sel_hi:[1,0]
	v_pk_fma_f32 v[16:17], v[64:65], v[24:25], v[80:81]
	v_pk_fma_f32 v[18:19], v[66:67], v[26:27], v[82:83]
	global_store_dwordx4 v[42:43], v[16:19], off nt
	v_pk_mul_f32 v[24:25], v[30:31], v[44:45] op_sel_hi:[1,0]
	v_pk_mul_f32 v[26:27], v[28:29], v[44:45] op_sel_hi:[1,0]
	v_cvt_pk_bf16_f32 v16, v16, v17
	v_cvt_pk_bf16_f32 v17, v18, v19
	global_store_dwordx2 v[40:41], v[16:17], off nt
	s_nop 0
	v_pk_fma_f32 v[16:17], v[68:69], v[26:27], v[84:85]
	v_pk_fma_f32 v[18:19], v[70:71], v[24:25], v[86:87]
	global_store_dwordx4 v[42:43], v[16:19], off offset:1024 nt
	v_pk_mul_f32 v[24:25], v[34:35], v[44:45] op_sel_hi:[1,0]
	v_pk_mul_f32 v[26:27], v[32:33], v[44:45] op_sel_hi:[1,0]
	v_cvt_pk_bf16_f32 v16, v16, v17
	v_cvt_pk_bf16_f32 v17, v18, v19
	global_store_dwordx2 v[40:41], v[16:17], off offset:512 nt
	s_nop 0
	v_pk_fma_f32 v[16:17], v[72:73], v[26:27], v[88:89]
	v_pk_fma_f32 v[18:19], v[74:75], v[24:25], v[90:91]
	global_store_dwordx4 v[42:43], v[16:19], off offset:2048 nt
	v_pk_mul_f32 v[24:25], v[38:39], v[44:45] op_sel_hi:[1,0]
	v_pk_mul_f32 v[26:27], v[36:37], v[44:45] op_sel_hi:[1,0]
	v_cvt_pk_bf16_f32 v16, v16, v17
	v_cvt_pk_bf16_f32 v17, v18, v19
	global_store_dwordx2 v[40:41], v[16:17], off offset:1024 nt
	s_nop 0
	v_pk_fma_f32 v[16:17], v[76:77], v[26:27], v[92:93]
	v_pk_fma_f32 v[18:19], v[78:79], v[24:25], v[94:95]
	global_store_dwordx4 v[42:43], v[16:19], off offset:3072 nt
	s_nop 1
	v_cvt_pk_bf16_f32 v16, v16, v17
	v_cvt_pk_bf16_f32 v17, v18, v19
	global_store_dwordx2 v[40:41], v[16:17], off offset:1536 nt
	s_cbranch_scc1 .LBB0_724
	v_readlane_b32 s81, v234, 49
